# v1 + double-buffered HGRN pass-2 state prefix loads + prologue_x row loop with next-row prefetch (were 1-4 loads in flight)
# speedup vs baseline: 1.0210x; 1.0014x over previous
; __device__ __forceinline__ float bflo(unsigned u) { return __uint_as_float(u << 16); }
; __device__ __forceinline__ float bfhi(unsigned u) { return __uint_as_float(u & 0xffff0000u); }
; __device__ __forceinline__ unsigned pk2(float lo, float hi) { f32x2 v = {lo, hi}; bf2_t b = __builtin_convertvector(v, bf2_t); return __builtin_bit_cast(unsigned, b); }
; __device__ __forceinline__ float shx(float v, int lane, int mask) { return __int_as_float(__builtin_amdgcn_ds_bpermute((lane ^ mask) << 2, __float_as_int(v))); }
; __device__ __forceinline__ unsigned pk_lo8(float a, float b, float c, float d) { int w = 0; w = __builtin_amdgcn_cvt_pk_fp8_f32(a * 512.f, b * 512.f, w, false); w = __builtin_amdgcn_cvt_pk_fp8_f32(c * 512.f, d * 512.f, w, true); return (unsigned)w; }
; __device__ __forceinline__ void prologue_x(int wv, const Args& a) {
;     ...
;     for (int m = gw; m < MTOK; m += NGW) {
;         const f32x4* xr = (const f32x4*)(a.in[0] + (size_t)m * DM) + lane;
;         u32x2* xb = (u32x2*)(XB + (size_t)m * DM) + lane; unsigned* xl = (unsigned*)((unsigned char*)(a.ws + WS_XL) + (size_t)m * DM) + lane;
;         float s = 0.f;
; #pragma unroll
;         for (int j = 0; j < 4; ++j) { const f32x4 v = xr[64 * j]; u32x2 w; w.x = pk2(v[0], v[1]); w.y = pk2(v[2], v[3]); xb[64 * j] = w; xl[64 * j] = pk_lo8(v[0] - bflo(w.x), v[1] - bfhi(w.x), v[2] - bflo(w.y), v[3] - bfhi(w.y)); s += (v[0] * v[0] + v[1] * v[1]) + (v[2] * v[2] + v[3] * v[3]); }
; #pragma unroll
;         for (int o = 1; o < 64; o <<= 1) s += shx(s, lane, o);
;         if (lane == 0) ssq[m] = s;
;     }
.LBB0_32:
	s_or_b64 exec, exec, s[6:7]
	v_ashrrev_i32_e32 v0, 6, v32
	s_lshl_b32 s0, s60, 3
	v_writelane_b32 v252, s0, 3
	v_add_u32_e32 v6, s0, v0
	s_mov_b32 s0, 0x8000
	v_cmp_gt_i32_e32 vcc, s0, v6
	s_and_saveexec_b64 s[6:7], vcc
	s_cbranch_execz .LBB0_37
	v_ashrrev_i32_e32 v7, 31, v6
	v_lshlrev_b32_e32 v4, 2, v33
	v_lshlrev_b64 v[2:3], 10, v[6:7]
	v_xor_b32_e32 v8, 4, v4
	v_xor_b32_e32 v9, 8, v4
	v_xor_b32_e32 v10, 16, v4
	v_xor_b32_e32 v11, 32, v4
	v_xor_b32_e32 v12, 64, v4
	v_xor_b32_e32 v13, 0x80, v4
	v_or_b32_e32 v2, v2, v4
	v_lshlrev_b64 v[4:5], 12, v[6:7]
	v_mov_b64_e32 v[0:1], 0x100000
	v_lshl_or_b32 v4, v33, 4, v4
	v_add_u32_e32 v14, 0xfffff800, v6
	v_lshl_add_u64 v[0:1], v[6:7], 2, v[0:1]
	s_waitcnt lgkmcnt(0)
	v_lshl_add_u64 v[4:5], s[2:3], 0, v[4:5]
	s_mov_b64 s[2:3], 0xc00
	v_lshlrev_b64 v[6:7], 11, v[6:7]
	v_cmp_eq_u32_e64 s[0:1], 0, v33
	v_lshl_add_u64 v[4:5], v[4:5], 0, s[2:3]
	v_lshl_or_b32 v6, v33, 3, v6
	s_mov_b64 s[8:9], 0
	s_mov_b32 s18, 0x4100000
	s_mov_b32 s19, 0x8100000
	s_mov_b64 s[10:11], 0x2000
	s_mov_b64 s[12:13], 0x200000
	s_mov_b64 s[14:15], 0x800000
	s_mov_b64 s[16:17], 0x400000
	s_movk_i32 s20, 0x77ff
	s_movk_i32 s21, 16
	s_add_u32 s22, s4, 0x4100000
	s_addc_u32 s23, s5, 0
	s_add_u32 s24, s4, 0x8100000
	s_addc_u32 s25, s5, 0
	global_load_dwordx4 v[40:43], v[4:5], off offset:-3072
	global_load_dwordx4 v[44:47], v[4:5], off offset:-2048
	global_load_dwordx4 v[48:51], v[4:5], off offset:-1024
	global_load_dwordx4 v[52:55], v[4:5], off
	s_waitcnt vmcnt(0)
.Lpx_loop:
	v_mov_b64_e32 v[16:17], v[40:41]
	v_mov_b64_e32 v[18:19], v[42:43]
	v_mov_b64_e32 v[20:21], v[44:45]
	v_mov_b64_e32 v[22:23], v[46:47]
	v_mov_b64_e32 v[24:25], v[48:49]
	v_mov_b64_e32 v[26:27], v[50:51]
	v_mov_b64_e32 v[28:29], v[52:53]
	v_mov_b64_e32 v[30:31], v[54:55]
	s_cmp_eq_u32 s21, 1
	s_cbranch_scc1 .Lpx_nonext
	v_lshl_add_u64 v[4:5], v[4:5], 0, s[14:15]
	global_load_dwordx4 v[40:43], v[4:5], off offset:-3072
	global_load_dwordx4 v[44:47], v[4:5], off offset:-2048
	global_load_dwordx4 v[48:51], v[4:5], off offset:-1024
	global_load_dwordx4 v[52:55], v[4:5], off
.Lpx_nonext:
	v_cvt_pk_bf16_f32 v56, v16, v17
	v_cvt_pk_bf16_f32 v57, v18, v19
	v_mov_b32_e32 v58, 0
	v_lshlrev_b32_e32 v60, 16, v56
	v_and_b32_e32 v61, 0xffff0000, v56
	v_lshlrev_b32_e32 v62, 16, v57
	v_and_b32_e32 v63, 0xffff0000, v57
	v_sub_f32_e32 v60, v16, v60
	v_sub_f32_e32 v61, v17, v61
	v_sub_f32_e32 v62, v18, v62
	v_sub_f32_e32 v63, v19, v63
	v_mul_f32_e32 v60, 0x44000000, v60
	v_mul_f32_e32 v61, 0x44000000, v61
	v_mul_f32_e32 v62, 0x44000000, v62
	v_mul_f32_e32 v63, 0x44000000, v63
	v_cvt_pk_fp8_f32 v58, v60, v61
	v_mul_f32_e32 v68, v17, v17
	v_mul_f32_e32 v69, v19, v19
	v_cvt_pk_fp8_f32 v58, v62, v63 op_sel:[0,0,1]
	v_fmac_f32_e32 v68, v16, v16
	v_fmac_f32_e32 v69, v18, v18
	global_store_dwordx2 v6, v[56:57], s[22:23]
	global_store_dword v2, v58, s[24:25]
	v_add_f32_e32 v59, v68, v69
	v_cvt_pk_bf16_f32 v56, v20, v21
	v_cvt_pk_bf16_f32 v57, v22, v23
	v_mov_b32_e32 v58, 0
	v_lshlrev_b32_e32 v60, 16, v56
	v_and_b32_e32 v61, 0xffff0000, v56
	v_lshlrev_b32_e32 v62, 16, v57
	v_and_b32_e32 v63, 0xffff0000, v57
	v_sub_f32_e32 v60, v20, v60
	v_sub_f32_e32 v61, v21, v61
	v_sub_f32_e32 v62, v22, v62
	v_sub_f32_e32 v63, v23, v63
	v_mul_f32_e32 v60, 0x44000000, v60
	v_mul_f32_e32 v61, 0x44000000, v61
	v_mul_f32_e32 v62, 0x44000000, v62
	v_mul_f32_e32 v63, 0x44000000, v63
	v_cvt_pk_fp8_f32 v58, v60, v61
	v_mul_f32_e32 v68, v21, v21
	v_mul_f32_e32 v69, v23, v23
	v_cvt_pk_fp8_f32 v58, v62, v63 op_sel:[0,0,1]
	v_fmac_f32_e32 v68, v20, v20
	v_fmac_f32_e32 v69, v22, v22
	global_store_dwordx2 v6, v[56:57], s[22:23] offset:512
	global_store_dword v2, v58, s[24:25] offset:256
	v_add_f32_e32 v68, v68, v69
	v_add_f32_e32 v59, v59, v68
	v_cvt_pk_bf16_f32 v56, v24, v25
	v_cvt_pk_bf16_f32 v57, v26, v27
	v_mov_b32_e32 v58, 0
	v_lshlrev_b32_e32 v60, 16, v56
	v_and_b32_e32 v61, 0xffff0000, v56
	v_lshlrev_b32_e32 v62, 16, v57
	v_and_b32_e32 v63, 0xffff0000, v57
	v_sub_f32_e32 v60, v24, v60
	v_sub_f32_e32 v61, v25, v61
	v_sub_f32_e32 v62, v26, v62
	v_sub_f32_e32 v63, v27, v63
	v_mul_f32_e32 v60, 0x44000000, v60
	v_mul_f32_e32 v61, 0x44000000, v61
	v_mul_f32_e32 v62, 0x44000000, v62
	v_mul_f32_e32 v63, 0x44000000, v63
	v_cvt_pk_fp8_f32 v58, v60, v61
	v_mul_f32_e32 v68, v25, v25
	v_mul_f32_e32 v69, v27, v27
	v_cvt_pk_fp8_f32 v58, v62, v63 op_sel:[0,0,1]
	v_fmac_f32_e32 v68, v24, v24
	v_fmac_f32_e32 v69, v26, v26
	global_store_dwordx2 v6, v[56:57], s[22:23] offset:1024
	global_store_dword v2, v58, s[24:25] offset:512
	v_add_f32_e32 v68, v68, v69
	v_add_f32_e32 v59, v59, v68
	v_cvt_pk_bf16_f32 v56, v28, v29
	v_cvt_pk_bf16_f32 v57, v30, v31
	v_mov_b32_e32 v58, 0
	v_lshlrev_b32_e32 v60, 16, v56
	v_and_b32_e32 v61, 0xffff0000, v56
	v_lshlrev_b32_e32 v62, 16, v57
	v_and_b32_e32 v63, 0xffff0000, v57
	v_sub_f32_e32 v60, v28, v60
	v_sub_f32_e32 v61, v29, v61
	v_sub_f32_e32 v62, v30, v62
	v_sub_f32_e32 v63, v31, v63
	v_mul_f32_e32 v60, 0x44000000, v60
	v_mul_f32_e32 v61, 0x44000000, v61
	v_mul_f32_e32 v62, 0x44000000, v62
	v_mul_f32_e32 v63, 0x44000000, v63
	v_cvt_pk_fp8_f32 v58, v60, v61
	v_mul_f32_e32 v68, v29, v29
	v_mul_f32_e32 v69, v31, v31
	v_cvt_pk_fp8_f32 v58, v62, v63 op_sel:[0,0,1]
	v_fmac_f32_e32 v68, v28, v28
	v_fmac_f32_e32 v69, v30, v30
	global_store_dwordx2 v6, v[56:57], s[22:23] offset:1536
	global_store_dword v2, v58, s[24:25] offset:768
	v_add_f32_e32 v68, v68, v69
	v_add_f32_e32 v59, v59, v68
	ds_bpermute_b32 v60, v8, v59
	s_waitcnt lgkmcnt(0)
	v_add_f32_e32 v59, v59, v60
	ds_bpermute_b32 v60, v9, v59
	s_waitcnt lgkmcnt(0)
	v_add_f32_e32 v59, v59, v60
	ds_bpermute_b32 v60, v10, v59
	s_waitcnt lgkmcnt(0)
	v_add_f32_e32 v59, v59, v60
	ds_bpermute_b32 v60, v11, v59
	s_waitcnt lgkmcnt(0)
	v_add_f32_e32 v59, v59, v60
	ds_bpermute_b32 v60, v12, v59
	s_waitcnt lgkmcnt(0)
	v_add_f32_e32 v59, v59, v60
	ds_bpermute_b32 v60, v13, v59
	s_waitcnt lgkmcnt(0)
	v_add_f32_e32 v59, v59, v60
	s_and_saveexec_b64 s[2:3], s[0:1]
	global_store_dword v0, v59, s[4:5]
	s_mov_b64 exec, s[2:3]
	v_lshl_add_u64 v[0:1], v[0:1], 0, s[10:11]
	v_lshl_add_u64 v[2:3], v[2:3], 0, s[12:13]
	v_lshl_add_u64 v[6:7], v[6:7], 0, s[16:17]
	s_sub_u32 s21, s21, 1
	s_cmp_eq_u32 s21, 0
	s_cbranch_scc1 .Lpx_end
	s_waitcnt vmcnt(9)
	s_branch .Lpx_loop
;     __device__ bool next(int i, Unit& u) const {
;         const long L = (long)i * G + c; if (L >= nwg) return false;
;         int wgid = (int)L; { const int q = nwg / NXCD, r = nwg % NXCD, xcd = wgid % NXCD, off = wgid / NXCD; wgid = (xcd < r ? xcd * (q + 1) : r * (q + 1) + (xcd - r) * q) + off; }
;         const int nig = WGM * nN, gid = wgid / nig, fm = gid * WGM, gsz = (nM - fm) < WGM ? (nM - fm) : WGM;
;         u.pm = fm + ((wgid % nig) % gsz); u.pn = (wgid % nig) / gsz; return true;
;     }
.Lpx_end:
.LBB0_37:
	s_or_b64 exec, exec, s[6:7]
	s_load_dwordx2 s[0:1], s[46:47], 0x90
	v_writelane_b32 v252, s46, 4
	s_cmpk_lt_i32 s60, 0xb00
	s_mul_i32 s8, s60, 12
	v_writelane_b32 v252, s47, 5
	s_waitcnt lgkmcnt(0)
	s_mul_i32 s0, s1, s0
	s_load_dword s1, s[46:47], 0x98
	s_movk_i32 s62, 0x121
	v_mov_b32_e32 v189, 0
	v_mov_b32_e32 v225, 1
	v_mov_b32_e32 v226, 0x358637bd
	s_waitcnt lgkmcnt(0)
	s_mul_i32 s81, s0, s1
	s_cselect_b64 s[0:1], -1, 0
	v_writelane_b32 v252, s0, 6
	s_ashr_i32 s61, s60, 31
	v_mov_b32_e32 v227, 6
	v_writelane_b32 v252, s1, 7
	s_lshr_b32 s0, s61, 29
	s_add_i32 s0, s60, s0
	s_ashr_i32 s6, s0, 3
	s_and_b32 s0, s0, -8
	s_sub_i32 s7, s60, s0
	s_cmpk_lt_i32 s60, 0x200
	s_cselect_b64 s[0:1], -1, 0
	s_lshl_b32 s4, s7, 6
	v_writelane_b32 v252, s0, 8
	s_cmpk_lt_i32 s60, 0x800
	v_mov_b64_e32 v[190:191], 0xb00
	v_writelane_b32 v252, s1, 9
	s_cselect_b64 s[0:1], -1, 0
	v_writelane_b32 v252, s0, 10
	s_lshl_b32 s5, s7, 8
	v_mov_b64_e32 v[192:193], 0xaff
	v_writelane_b32 v252, s1, 11
	s_ashr_i32 s0, s60, 6
	s_ashr_i32 s1, s0, 31
	s_lshl_b64 s[12:13], s[0:1], 13
	s_lshl_b32 s0, s60, 10
	s_and_b32 s0, s0, 0x1c00
	s_or_b32 s0, s12, s0
	v_writelane_b32 v252, s0, 12
	s_lshl_b32 s0, s60, 4
	s_and_b32 s59, s0, 0x380
	s_lshl_b64 s[0:1], s[60:61], 7
	v_writelane_b32 v252, s0, 13
	v_mov_b64_e32 v[194:195], 0x200
	v_mov_b64_e32 v[196:197], 0x1ff
	v_writelane_b32 v252, s1, 14
	s_lshl_b64 s[0:1], s[60:61], 9
	v_writelane_b32 v252, s0, 15
	v_mov_b32_e32 v237, 0x41b17218
	v_mov_b32_e32 v238, 0xff800000
	v_writelane_b32 v252, s1, 16
	s_and_b32 s1, s60, 7
	s_lshl_b32 s0, s1, 10
	s_or_b32 s12, s12, s0
	s_cmp_lg_u32 s1, 0
	v_writelane_b32 v252, s1, 17
	s_cselect_b64 s[0:1], -1, 0
	v_writelane_b32 v252, s0, 18
	s_movk_i32 s77, 0x84
	s_movk_i32 s63, 0x60
	v_writelane_b32 v252, s1, 19
	s_and_b32 s0, s60, -8
	s_cmpk_lt_i32 s60, 0x900
	s_cselect_b64 s[2:3], -1, 0
	v_writelane_b32 v252, s2, 20
	s_ashr_i32 s9, s8, 8
	s_and_b32 s1, s8, 60
	v_writelane_b32 v252, s3, 21
	s_mul_hi_i32 s2, s9, 0x55555556
	s_lshr_b32 s10, s2, 31
	s_add_i32 s2, s2, s10
	s_mul_i32 s10, s2, 3
	s_sub_i32 s9, s9, s10
	s_lshl_b32 s11, s9, 1
	s_lshl_b32 s10, 1, s11
	v_writelane_b32 v252, s10, 22
	s_lshr_b32 s10, 64, s11
	v_writelane_b32 v252, s11, 23
	s_sub_i32 s11, 6, s11
	s_add_i32 s10, s10, -1
	s_bfe_u32 s3, s8, 0x20006
	s_lshr_b32 s11, s1, s11
	s_and_b32 s10, s10, s1
	s_lshl_b32 s1, s9, 2
	s_or_b32 s14, s1, s3
	s_ashr_i32 s3, s2, 31
	s_lshl_b64 s[2:3], s[2:3], 13
	s_or_b32 s2, s2, s11
	v_writelane_b32 v252, s2, 24
	s_cmp_lg_u32 s10, 0
	s_mov_b32 s82, 0x40000
	v_writelane_b32 v252, s3, 25
	s_cselect_b64 s[2:3], -1, 0
	v_writelane_b32 v252, s2, 26
	s_lshl_b32 s1, s10, 7
	s_ashr_i32 s15, s14, 31
	v_writelane_b32 v252, s3, 27
	v_writelane_b32 v252, s10, 28
	v_writelane_b32 v252, s1, 29
	s_addk_i32 s1, 0xff80
	s_lshl_b32 s2, s14, 7
	v_writelane_b32 v252, s1, 30
	s_ashr_i32 s3, s2, 31
	v_writelane_b32 v252, s2, 31
	s_cmp_lt_i32 s7, 0
	s_mul_i32 s1, s7, 0x41
	v_writelane_b32 v252, s3, 32
	s_movk_i32 s3, 0x161
	s_cselect_b32 s3, s3, 0x160
	s_mul_i32 s2, s7, 0x101
	s_mul_i32 s3, s7, s3
	s_cselect_b32 s1, s1, s4
	s_cselect_b32 s4, s2, s5
	s_cselect_b32 s9, s62, 0x120
	s_add_i32 s3, s3, s6
	s_mul_hi_i32 s2, s3, 0x2e8ba2e9
	s_lshr_b32 s5, s2, 31
	s_ashr_i32 s2, s2, 5
	s_add_i32 s2, s2, s5
	s_mul_i32 s5, s2, 0xb0
	s_sub_i32 s3, s3, s5
	s_lshl_b32 s10, s2, 3
	s_bfe_u32 s2, s3, 0x3001c
	s_add_i32 s5, s3, s2
	s_sext_i32_i16 s11, s5
	s_and_b32 s5, s5, 0xfff8
	s_sub_i32 s3, s3, s5
	v_writelane_b32 v252, s14, 33
	s_sext_i32_i16 s3, s3
	s_lshr_b32 s2, s11, 3
	v_writelane_b32 v252, s15, 34
	s_add_i32 s14, s10, s3
	s_ashr_i32 s3, s11, 3
	v_writelane_b32 v252, s3, 35
	s_mov_b32 s10, s14
	s_ashr_i32 s15, s14, 31
	v_writelane_b32 v252, s10, 36
	s_bfe_i64 s[2:3], s[2:3], 0x100000
	s_lshl_b64 s[2:3], s[2:3], 19
	v_writelane_b32 v252, s11, 37
	s_lshl_b64 s[10:11], s[14:15], 19
	v_writelane_b32 v252, s10, 38
	s_add_i32 s1, s1, s6
	s_mov_b32 s83, 0x18000
	v_writelane_b32 v252, s11, 39
	v_writelane_b32 v252, s2, 40
	s_movk_i32 s64, 0x2000
	s_mov_b32 s84, 0x10000
	v_writelane_b32 v252, s3, 41
	s_ashr_i32 s2, s1, 31
	s_lshr_b32 s2, s2, 27
	s_add_i32 s2, s1, s2
	s_ashr_i32 s3, s2, 5
	s_and_b32 s2, s2, 0xffe0
	s_sub_i32 s1, s1, s2
	s_bfe_i32 s2, s1, 0x80000
	s_bfe_u32 s2, s2, 0x3000c
	s_add_i32 s5, s1, s2
	s_bfe_i32 s2, s5, 0x80000
	s_and_b32 s5, s5, 0xf8
	s_sub_i32 s1, s1, s5
	s_lshl_b32 s3, s3, 3
;     __device__ bool next(int i, Unit& u) const {
;         const long L = (long)i * G + c; if (L >= nwg) return false;
;         int wgid = (int)L; { const int q = nwg / NXCD, r = nwg % NXCD, xcd = wgid % NXCD, off = wgid / NXCD; wgid = (xcd < r ? xcd * (q + 1) : r * (q + 1) + (xcd - r) * q) + off; }
;         const int nig = WGM * nN, gid = wgid / nig, fm = gid * WGM, gsz = (nM - fm) < WGM ? (nM - fm) : WGM;
;         u.pm = fm + ((wgid % nig) % gsz); u.pn = (wgid % nig) / gsz; return true;
;     }
	s_sext_i32_i8 s1, s1
	s_add_i32 s14, s3, s1
	s_add_i32 s1, s4, s6
	s_ashr_i32 s3, s1, 31
	s_lshr_b32 s3, s3, 25
	s_add_i32 s3, s1, s3
	s_ashr_i32 s4, s3, 7
	s_and_b32 s3, s3, 0xff80
	s_sub_i32 s1, s1, s3
	s_bfe_i32 s3, s1, 0x80000
	s_bfe_u32 s3, s3, 0x3000c
	s_add_i32 s3, s1, s3
	s_lshl_b32 s5, s4, 3
	s_bfe_i32 s4, s3, 0x80000
	s_and_b32 s3, s3, 0xf8
	s_sext_i32_i16 s10, s2
	s_sub_i32 s1, s1, s3
	s_lshr_b32 s2, s10, 3
	s_ashr_i32 s11, s10, 3
	s_sext_i32_i16 s10, s4
	s_sext_i32_i8 s1, s1
	s_add_i32 s16, s5, s1
	s_ashr_i32 s1, s10, 3
	s_lshr_b32 s4, s10, 3
	v_writelane_b32 v252, s1, 42
	s_mov_b32 s10, s16
	s_ashr_i32 s17, s16, 31
	v_writelane_b32 v252, s10, 43
	s_lshl_b64 s[16:17], s[16:17], 19
	s_bfe_i64 s[4:5], s[4:5], 0x100000
	v_writelane_b32 v252, s11, 44
	v_writelane_b32 v252, s16, 45
	s_mul_i32 s1, s7, s9
	s_lshl_b64 s[4:5], s[4:5], 19
	v_writelane_b32 v252, s17, 46
	s_add_i32 s1, s1, s6
	v_writelane_b32 v252, s4, 47
	s_mul_hi_i32 s3, s1, 0x38e38e39
	s_ashr_i32 s15, s14, 31
	v_writelane_b32 v252, s5, 48
	s_lshr_b32 s4, s3, 31
	s_ashr_i32 s3, s3, 5
	s_add_i32 s3, s3, s4
	s_lshl_b32 s5, s3, 3
	s_mulk_i32 s3, 0x90
	s_sub_i32 s1, s1, s3
	s_bfe_u32 s3, s1, 0x3001c
	s_add_i32 s3, s1, s3
	s_sext_i32_i16 s6, s3
	s_and_b32 s3, s3, 0xfff8
	s_sub_i32 s1, s1, s3
	s_sext_i32_i16 s1, s1
	s_add_i32 s16, s5, s1
	s_ashr_i32 s1, s6, 3
	s_lshr_b32 s4, s6, 3
	v_writelane_b32 v252, s1, 49
	s_lshl_b64 s[6:7], s[14:15], 19
	v_writelane_b32 v252, s6, 50
	s_bfe_i64 s[2:3], s[2:3], 0x100000
	s_ashr_i32 s17, s16, 31
	v_writelane_b32 v252, s7, 51
	s_lshl_b64 s[6:7], s[2:3], 19
	v_writelane_b32 v252, s6, 52
	s_lshl_b64 s[2:3], s[2:3], 18
	s_ashr_i32 s1, s0, 31
	v_writelane_b32 v252, s7, 53
	s_lshl_b64 s[6:7], s[14:15], 18
	v_writelane_b32 v252, s6, 54
	s_mov_b32 s85, 0x8000
	s_mov_b32 s65, 0xa000
	v_writelane_b32 v252, s7, 55
	v_writelane_b32 v252, s2, 56
	s_lshl_b32 s6, s11, 1
	s_ashr_i32 s7, s6, 31
	v_writelane_b32 v252, s3, 57
	s_mov_b32 s2, s6
	v_writelane_b32 v252, s2, 58
	s_movk_i32 s54, 0x80
	s_mov_b32 s33, 0x800000
	v_writelane_b32 v252, s3, 59
	s_lshl_b64 s[2:3], s[6:7], 18
	v_writelane_b32 v252, s2, 60
	s_mov_b32 s66, 0xb000
	s_mov_b32 s88, 0x48000
	v_writelane_b32 v252, s3, 61
	s_mov_b32 s2, s16
	v_writelane_b32 v252, s2, 62
	s_mov_b32 s89, 0x50000
	s_movk_i32 s68, 0x7f
	v_writelane_b32 v252, s3, 63
	s_lshl_b64 s[2:3], s[16:17], 19
	v_writelane_b32 v253, s2, 0
	s_movk_i32 s67, 0x1000
	s_mov_b32 s92, 0x7f800000
	v_writelane_b32 v253, s3, 1
	s_bfe_i64 s[2:3], s[4:5], 0x100000
	s_lshl_b64 s[2:3], s[2:3], 19
	v_writelane_b32 v253, s2, 2
	s_movk_i32 s55, 0x48
	s_mov_b32 s93, 0x3f317217
	v_writelane_b32 v253, s3, 3
	s_lshl_b64 s[2:3], s[0:1], 9
	s_add_u32 s2, s2, 0x1d100000
	v_writelane_b32 v253, s2, 4
	s_addc_u32 s2, s3, 0
	v_writelane_b32 v253, s2, 5
	s_lshl_b64 s[0:1], s[0:1], 7
	v_writelane_b32 v253, s0, 6
	s_add_i32 s69, 0, 0x20800
	s_add_i32 s70, 0, 0x21000
	v_writelane_b32 v253, s1, 7
	s_lshl_b32 s0, s60, 5
	s_and_b32 s1, s0, 0x700
	s_or_b32 s0, s8, 1
	v_writelane_b32 v253, s0, 8
	v_writelane_b32 v253, s12, 9
	s_mov_b32 s0, s13
	s_add_i32 s71, 0, 0x11400
	v_writelane_b32 v253, s13, 10
	v_writelane_b32 v253, s0, 11
	s_mul_hi_i32 s0, s14, 0x160000
	v_writelane_b32 v253, s0, 12
	s_mov_b32 s0, s14
	v_writelane_b32 v253, s0, 13
	s_movk_i32 s78, 0x110
	s_movk_i32 s80, 0xc00
	v_writelane_b32 v253, s1, 14
	s_mul_i32 s0, s14, 0x160000
	v_writelane_b32 v253, s0, 15
	s_mul_hi_i32 s0, s11, 0x160000
	v_writelane_b32 v253, s0, 16
	v_writelane_b32 v253, s11, 17
	s_mul_i32 s0, s11, 0x160000
	v_writelane_b32 v253, s0, 18
	v_writelane_b32 v253, s1, 19
	s_or_b32 s0, s1, 0x18100040
	v_writelane_b32 v253, s0, 20
	s_lshl_b32 s0, s60, 12
	v_writelane_b32 v253, s0, 21
	s_add_i32 s0, 0, 0x23ff0
	v_writelane_b32 v253, s0, 22
	s_add_i32 s0, 0, 0x23ff4
	v_writelane_b32 v253, s0, 23
	s_add_i32 s0, 0, 0x21200
	v_writelane_b32 v253, s0, 24
	s_add_i32 s0, 0, 0x15c00
	v_writelane_b32 v253, s0, 25
	v_writelane_b32 v253, s60, 26
	s_movk_i32 s79, 0x3000
	s_mov_b32 s86, 0x9000
	v_writelane_b32 v253, s61, 27
	v_writelane_b32 v253, s59, 28
	v_writelane_b32 v253, s69, 29
	v_writelane_b32 v253, s70, 30
	s_add_i32 s94, 0, 0x11000
	s_mov_b32 s44, 0
	s_mov_b32 s73, 0
	s_mov_b64 s[2:3], 0
	s_mov_b64 s[24:25], -1
	s_mov_b64 s[90:91], 0x58000
	s_mov_b64 s[96:97], 0x1000
	s_mov_b64 s[74:75], 0x80
	s_mov_b64 s[56:57], 0x10000
	s_mov_b32 s76, 0x3b000000
	v_writelane_b32 v253, s71, 31
	s_branch .LBB0_41

; template <bool FULL>
; __device__ __forceinline__ void hgrn_pass(int wv, const Args& a, int l, LAS unsigned char* lds, int item, bool dmy) {
;     ...
;     if (FULL) {
;         for (int pp = 0; pp < p; ++pp) {
;             const int it2 = item - p + pp;
;             const f32x4 dd = *(const f32x4*)(DT + (size_t)it2 * 128 + wid * 16 + 4 * fq);
; #pragma unroll
;             for (int j = 0; j < 8; ++j)
; #pragma unroll
;                 for (int r = 0; r < 4; ++r) sacc[j][r] = sacc[j][r] * dd[r] + US[((size_t)it2 * 128 + wid * 16 + 4 * fq + r) * 128 + j * 16 + fr];
;         }
.LBB0_470:
	s_mov_b64 s[2:3], 0x200
	global_load_dwordx4 v[90:93], v[36:37], off
	global_load_dword v94, v[38:39], off offset:-1024
	global_load_dword v95, v[38:39], off offset:-512
	global_load_dword v96, v[38:39], off
	global_load_dword v97, v[38:39], off offset:512
	global_load_dword v98, v[38:39], off offset:-960
	global_load_dword v99, v[38:39], off offset:-448
	global_load_dword v100, v[38:39], off offset:64
	global_load_dword v101, v[38:39], off offset:576
	global_load_dword v102, v[38:39], off offset:-896
	global_load_dword v103, v[38:39], off offset:-384
	global_load_dword v104, v[38:39], off offset:128
	global_load_dword v105, v[38:39], off offset:640
	global_load_dword v106, v[38:39], off offset:-832
	global_load_dword v107, v[38:39], off offset:-320
	global_load_dword v108, v[38:39], off offset:192
	global_load_dword v109, v[38:39], off offset:704
	global_load_dword v110, v[38:39], off offset:-768
	global_load_dword v111, v[38:39], off offset:-256
	global_load_dword v112, v[38:39], off offset:256
	global_load_dword v113, v[38:39], off offset:768
	global_load_dword v114, v[38:39], off offset:-704
	global_load_dword v115, v[38:39], off offset:-192
	global_load_dword v116, v[38:39], off offset:320
	global_load_dword v117, v[38:39], off offset:832
	global_load_dword v118, v[38:39], off offset:-640
	global_load_dword v119, v[38:39], off offset:-128
	global_load_dword v120, v[38:39], off offset:384
	global_load_dword v121, v[38:39], off offset:896
	global_load_dword v122, v[38:39], off offset:-576
	global_load_dword v123, v[38:39], off offset:-64
	global_load_dword v124, v[38:39], off offset:448
	global_load_dword v125, v[38:39], off offset:960
	v_lshl_add_u64 v[36:37], v[36:37], 0, s[2:3]
	v_lshl_add_u64 v[38:39], v[38:39], 0, s[56:57]
.Lhgp_loop:
	s_add_i32 s0, s0, -1
	s_cmp_eq_u32 s0, 0
	s_cbranch_scc1 .Lhgp_lastA
	global_load_dwordx4 v[126:129], v[36:37], off
	global_load_dword v130, v[38:39], off offset:-1024
	global_load_dword v131, v[38:39], off offset:-512
	global_load_dword v132, v[38:39], off
	global_load_dword v133, v[38:39], off offset:512
	global_load_dword v134, v[38:39], off offset:-960
	global_load_dword v135, v[38:39], off offset:-448
	global_load_dword v136, v[38:39], off offset:64
	global_load_dword v137, v[38:39], off offset:576
	global_load_dword v138, v[38:39], off offset:-896
	global_load_dword v139, v[38:39], off offset:-384
	global_load_dword v140, v[38:39], off offset:128
	global_load_dword v141, v[38:39], off offset:640
	global_load_dword v142, v[38:39], off offset:-832
	global_load_dword v143, v[38:39], off offset:-320
	global_load_dword v144, v[38:39], off offset:192
	global_load_dword v145, v[38:39], off offset:704
	global_load_dword v146, v[38:39], off offset:-768
	global_load_dword v147, v[38:39], off offset:-256
	global_load_dword v148, v[38:39], off offset:256
	global_load_dword v149, v[38:39], off offset:768
	global_load_dword v150, v[38:39], off offset:-704
	global_load_dword v151, v[38:39], off offset:-192
	global_load_dword v152, v[38:39], off offset:320
	global_load_dword v153, v[38:39], off offset:832
	global_load_dword v154, v[38:39], off offset:-640
	global_load_dword v155, v[38:39], off offset:-128
	global_load_dword v156, v[38:39], off offset:384
	global_load_dword v157, v[38:39], off offset:896
	global_load_dword v158, v[38:39], off offset:-576
	global_load_dword v159, v[38:39], off offset:-64
	global_load_dword v160, v[38:39], off offset:448
	global_load_dword v161, v[38:39], off offset:960
	v_lshl_add_u64 v[36:37], v[36:37], 0, s[2:3]
	v_lshl_add_u64 v[38:39], v[38:39], 0, s[56:57]
	s_waitcnt vmcnt(33)
	v_pk_fma_f32 v[0:1], v[0:1], v[90:91], v[94:95]
	v_pk_fma_f32 v[2:3], v[2:3], v[92:93], v[96:97]
	v_pk_fma_f32 v[4:5], v[4:5], v[90:91], v[98:99]
	v_pk_fma_f32 v[6:7], v[6:7], v[92:93], v[100:101]
	v_pk_fma_f32 v[8:9], v[8:9], v[90:91], v[102:103]
	v_pk_fma_f32 v[10:11], v[10:11], v[92:93], v[104:105]
	v_pk_fma_f32 v[12:13], v[12:13], v[90:91], v[106:107]
	v_pk_fma_f32 v[14:15], v[14:15], v[92:93], v[108:109]
	v_pk_fma_f32 v[16:17], v[16:17], v[90:91], v[110:111]
	v_pk_fma_f32 v[18:19], v[18:19], v[92:93], v[112:113]
	v_pk_fma_f32 v[20:21], v[20:21], v[90:91], v[114:115]
	v_pk_fma_f32 v[22:23], v[22:23], v[92:93], v[116:117]
	v_pk_fma_f32 v[24:25], v[24:25], v[90:91], v[118:119]
	v_pk_fma_f32 v[26:27], v[26:27], v[92:93], v[120:121]
	v_pk_fma_f32 v[28:29], v[28:29], v[90:91], v[122:123]
	v_pk_fma_f32 v[30:31], v[30:31], v[92:93], v[124:125]
	s_add_i32 s0, s0, -1
	s_cmp_eq_u32 s0, 0
	s_cbranch_scc1 .Lhgp_lastB
; template <bool FULL>
; __device__ __forceinline__ void hgrn_pass(int wv, const Args& a, int l, LAS unsigned char* lds, int item, bool dmy) {
;     ...
;     if (FULL) {
;         for (int pp = 0; pp < p; ++pp) {
;             const int it2 = item - p + pp;
;             const f32x4 dd = *(const f32x4*)(DT + (size_t)it2 * 128 + wid * 16 + 4 * fq);
; #pragma unroll
;             for (int j = 0; j < 8; ++j)
; #pragma unroll
;                 for (int r = 0; r < 4; ++r) sacc[j][r] = sacc[j][r] * dd[r] + US[((size_t)it2 * 128 + wid * 16 + 4 * fq + r) * 128 + j * 16 + fr];
;         }
	global_load_dwordx4 v[90:93], v[36:37], off
	global_load_dword v94, v[38:39], off offset:-1024
	global_load_dword v95, v[38:39], off offset:-512
	global_load_dword v96, v[38:39], off
	global_load_dword v97, v[38:39], off offset:512
	global_load_dword v98, v[38:39], off offset:-960
	global_load_dword v99, v[38:39], off offset:-448
	global_load_dword v100, v[38:39], off offset:64
	global_load_dword v101, v[38:39], off offset:576
	global_load_dword v102, v[38:39], off offset:-896
	global_load_dword v103, v[38:39], off offset:-384
	global_load_dword v104, v[38:39], off offset:128
	global_load_dword v105, v[38:39], off offset:640
	global_load_dword v106, v[38:39], off offset:-832
	global_load_dword v107, v[38:39], off offset:-320
	global_load_dword v108, v[38:39], off offset:192
	global_load_dword v109, v[38:39], off offset:704
	global_load_dword v110, v[38:39], off offset:-768
	global_load_dword v111, v[38:39], off offset:-256
	global_load_dword v112, v[38:39], off offset:256
	global_load_dword v113, v[38:39], off offset:768
	global_load_dword v114, v[38:39], off offset:-704
	global_load_dword v115, v[38:39], off offset:-192
	global_load_dword v116, v[38:39], off offset:320
	global_load_dword v117, v[38:39], off offset:832
	global_load_dword v118, v[38:39], off offset:-640
	global_load_dword v119, v[38:39], off offset:-128
	global_load_dword v120, v[38:39], off offset:384
	global_load_dword v121, v[38:39], off offset:896
	global_load_dword v122, v[38:39], off offset:-576
	global_load_dword v123, v[38:39], off offset:-64
	global_load_dword v124, v[38:39], off offset:448
	global_load_dword v125, v[38:39], off offset:960
	v_lshl_add_u64 v[36:37], v[36:37], 0, s[2:3]
	v_lshl_add_u64 v[38:39], v[38:39], 0, s[56:57]
	s_waitcnt vmcnt(33)
	v_pk_fma_f32 v[0:1], v[0:1], v[126:127], v[130:131]
	v_pk_fma_f32 v[2:3], v[2:3], v[128:129], v[132:133]
	v_pk_fma_f32 v[4:5], v[4:5], v[126:127], v[134:135]
	v_pk_fma_f32 v[6:7], v[6:7], v[128:129], v[136:137]
	v_pk_fma_f32 v[8:9], v[8:9], v[126:127], v[138:139]
	v_pk_fma_f32 v[10:11], v[10:11], v[128:129], v[140:141]
	v_pk_fma_f32 v[12:13], v[12:13], v[126:127], v[142:143]
	v_pk_fma_f32 v[14:15], v[14:15], v[128:129], v[144:145]
	v_pk_fma_f32 v[16:17], v[16:17], v[126:127], v[146:147]
	v_pk_fma_f32 v[18:19], v[18:19], v[128:129], v[148:149]
	v_pk_fma_f32 v[20:21], v[20:21], v[126:127], v[150:151]
	v_pk_fma_f32 v[22:23], v[22:23], v[128:129], v[152:153]
	v_pk_fma_f32 v[24:25], v[24:25], v[126:127], v[154:155]
	v_pk_fma_f32 v[26:27], v[26:27], v[128:129], v[156:157]
	v_pk_fma_f32 v[28:29], v[28:29], v[126:127], v[158:159]
	v_pk_fma_f32 v[30:31], v[30:31], v[128:129], v[160:161]
	s_branch .Lhgp_loop
.Lhgp_lastA:
	s_waitcnt vmcnt(0)
	v_pk_fma_f32 v[0:1], v[0:1], v[90:91], v[94:95]
	v_pk_fma_f32 v[2:3], v[2:3], v[92:93], v[96:97]
	v_pk_fma_f32 v[4:5], v[4:5], v[90:91], v[98:99]
	v_pk_fma_f32 v[6:7], v[6:7], v[92:93], v[100:101]
	v_pk_fma_f32 v[8:9], v[8:9], v[90:91], v[102:103]
	v_pk_fma_f32 v[10:11], v[10:11], v[92:93], v[104:105]
	v_pk_fma_f32 v[12:13], v[12:13], v[90:91], v[106:107]
	v_pk_fma_f32 v[14:15], v[14:15], v[92:93], v[108:109]
	v_pk_fma_f32 v[16:17], v[16:17], v[90:91], v[110:111]
	v_pk_fma_f32 v[18:19], v[18:19], v[92:93], v[112:113]
	v_pk_fma_f32 v[20:21], v[20:21], v[90:91], v[114:115]
	v_pk_fma_f32 v[22:23], v[22:23], v[92:93], v[116:117]
	v_pk_fma_f32 v[24:25], v[24:25], v[90:91], v[118:119]
	v_pk_fma_f32 v[26:27], v[26:27], v[92:93], v[120:121]
	v_pk_fma_f32 v[28:29], v[28:29], v[90:91], v[122:123]
	v_pk_fma_f32 v[30:31], v[30:31], v[92:93], v[124:125]
	s_branch .Lhgp_done
.Lhgp_lastB:
	s_waitcnt vmcnt(0)
	v_pk_fma_f32 v[0:1], v[0:1], v[126:127], v[130:131]
	v_pk_fma_f32 v[2:3], v[2:3], v[128:129], v[132:133]
	v_pk_fma_f32 v[4:5], v[4:5], v[126:127], v[134:135]
	v_pk_fma_f32 v[6:7], v[6:7], v[128:129], v[136:137]
	v_pk_fma_f32 v[8:9], v[8:9], v[126:127], v[138:139]
	v_pk_fma_f32 v[10:11], v[10:11], v[128:129], v[140:141]
	v_pk_fma_f32 v[12:13], v[12:13], v[126:127], v[142:143]
	v_pk_fma_f32 v[14:15], v[14:15], v[128:129], v[144:145]
	v_pk_fma_f32 v[16:17], v[16:17], v[126:127], v[146:147]
	v_pk_fma_f32 v[18:19], v[18:19], v[128:129], v[148:149]
	v_pk_fma_f32 v[20:21], v[20:21], v[126:127], v[150:151]
	v_pk_fma_f32 v[22:23], v[22:23], v[128:129], v[152:153]
	v_pk_fma_f32 v[24:25], v[24:25], v[126:127], v[154:155]
	v_pk_fma_f32 v[26:27], v[26:27], v[128:129], v[156:157]
	v_pk_fma_f32 v[28:29], v[28:29], v[126:127], v[158:159]
	v_pk_fma_f32 v[30:31], v[30:31], v[128:129], v[160:161]
.Lhgp_done:
	s_branch .LBB0_473
